# combine loop software pipelining: second token's 8 loads (renamed to v50-v92, clamped index) issued before the first token's math; waits recounted (on top of v54)
# baseline (speedup 1.0000x reference)
; DI float fast_exp2(float x) { return __builtin_amdgcn_exp2f(x); }
; DI void moba_combine_token(bf16_t* act, const unsigned* sel, const float* ml, int tok, int lane) {
;     const int hh = lane >> 3, ch = lane & 7;
;     const int b = tok >> 13, qpos = tok & (SEQ - 1);
;     bf16_t* rowp = act + (size_t)tok * PITCH;
;     const unsigned word = sel[(size_t)(b * 8 + hh) * SEQ + qpos];
;     const f32x4* mlp = (const f32x4*)(ml + ((size_t)tok * 8 + hh) * 8);
;     const f32x4 a = mlp[0], c = mlp[1];
;     const u32x4 v3 = *(const u32x4*)(rowp + C_KC + hh * 64 + ch * 8);
;     u32x4 vs[3];
; #pragma unroll
;     for (int s = 0; s < 3; ++s) vs[s] = *(const u32x4*)(rowp + C_KA + (s * 8 + hh) * 64 + ch * 8);
;     const u32x4 g = *(const u32x4*)(rowp + C_GB + hh * 64 + ch * 8);
;     const int ns = __popc(word);
;     const float m0 = ns > 0 ? a.x : NEG_INF, m1 = ns > 1 ? a.z : NEG_INF, m2 = ns > 2 ? c.x : NEG_INF, m3 = c.z;
;     const float M = fmaxf(fmaxf(m0, m1), fmaxf(m2, m3));
;     const float w0 = ns > 0 ? a.y * fast_exp2(m0 - M) : 0.f, w1 = ns > 1 ? a.w * fast_exp2(m1 - M) : 0.f, w2 = ns > 2 ? c.y * fast_exp2(m2 - M) : 0.f, w3 = c.w * fast_exp2(m3 - M);
; __global__ void __launch_bounds__(512, 2) hybrid_fwd(Params p) {
;     ...
;             for (int tok = gw; tok < T; tok += 2 * NGW) {
;                 moba_combine_token(act, (const unsigned*)(ws + WS_SEL), (const float*)(ws + WS_ML), tok, lane);
;                 if (tok + NGW < T) moba_combine_token(act, (const unsigned*)(ws + WS_SEL), (const float*)(ws + WS_ML), tok + NGW, lane);
.LBB0_583:
	s_and_b32 s14, s8, 0x1fff
	s_ashr_i32 s9, s8, 31
	s_mul_i32 s12, s8, 0x3200
	s_mul_hi_i32 s13, s8, 0x3200
	s_add_u32 s12, s10, s12
	s_addc_u32 s13, s11, s13
	s_ashr_i32 s15, s8, 10
	v_and_or_b32 v2, s15, -8, v13
	v_ashrrev_i32_e32 v3, 31, v2
	v_lshlrev_b64 v[2:3], 15, v[2:3]
	v_lshl_add_u64 v[2:3], s[6:7], 0, v[2:3]
	s_lshl_b32 s38, s14, 2
	v_lshl_add_u64 v[2:3], v[2:3], 0, s[38:39]
	global_load_dword v22, v[2:3], off
	s_lshl_b64 s[14:15], s[8:9], 8
	v_lshl_add_u64 v[2:3], v[10:11], 0, s[14:15]
	global_load_dwordx4 v[28:31], v[2:3], off offset:16
	global_load_dwordx4 v[18:21], v[2:3], off
	v_lshlrev_b32_e32 v0, 1, v12
	v_mov_b32_e32 v15, v1
	v_lshl_add_u64 v[2:3], s[12:13], 0, v[0:1]
	v_lshl_add_u64 v[2:3], v[2:3], 0, v[14:15]
	v_add_co_u32_e32 v4, vcc, s23, v2
	s_add_i32 s8, s8, s91
	s_nop 0
	v_addc_co_u32_e32 v5, vcc, 0, v3, vcc
	global_load_dwordx4 v[6:9], v[4:5], off offset:1024
	v_lshl_add_u64 v[4:5], s[12:13], 0, v[14:15]
	v_lshl_add_u64 v[4:5], v[4:5], 0, v[0:1]
	global_load_dwordx4 v[32:35], v[4:5], off offset:1024
	global_load_dwordx4 v[36:39], v[4:5], off offset:2048
	global_load_dwordx4 v[40:43], v[4:5], off offset:3072
	v_add_co_u32_e32 v16, vcc, s34, v2
	s_cmpk_gt_i32 s8, 0x7fff
	s_nop 0
	v_addc_co_u32_e32 v17, vcc, 0, v3, vcc
	global_load_dwordx4 v[2:5], v[16:17], off offset:3072
	s_min_i32 s98, s8, 0x7fff
	s_and_b32 s14, s98, 0x1fff
	s_ashr_i32 s99, s98, 31
	s_mul_i32 s12, s98, 0x3200
	s_mul_hi_i32 s13, s98, 0x3200
	s_add_u32 s12, s10, s12
	s_addc_u32 s13, s11, s13
	s_ashr_i32 s15, s98, 10
	v_and_or_b32 v50, s15, -8, v13
	v_ashrrev_i32_e32 v51, 31, v50
	v_lshlrev_b64 v[50:51], 15, v[50:51]
	v_lshl_add_u64 v[50:51], s[6:7], 0, v[50:51]
	s_lshl_b32 s38, s14, 2
	v_lshl_add_u64 v[50:51], v[50:51], 0, s[38:39]
	global_load_dword v70, v[50:51], off
	s_lshl_b64 s[14:15], s[98:99], 8
	v_lshl_add_u64 v[50:51], v[10:11], 0, s[14:15]
	global_load_dwordx4 v[74:77], v[50:51], off offset:16
	global_load_dwordx4 v[66:69], v[50:51], off
	v_lshl_add_u64 v[50:51], s[12:13], 0, v[0:1]
	v_lshl_add_u64 v[50:51], v[50:51], 0, v[14:15]
	v_add_co_u32_e32 v52, vcc, s23, v50
	s_nop 1
	v_addc_co_u32_e32 v53, vcc, 0, v51, vcc
	global_load_dwordx4 v[54:57], v[52:53], off offset:1024
	v_lshl_add_u64 v[52:53], s[12:13], 0, v[14:15]
	v_lshl_add_u64 v[52:53], v[52:53], 0, v[0:1]
	global_load_dwordx4 v[78:81], v[52:53], off offset:1024
	global_load_dwordx4 v[82:85], v[52:53], off offset:2048
	global_load_dwordx4 v[86:89], v[52:53], off offset:3072
	v_add_co_u32_e32 v64, vcc, s34, v50
	s_nop 1
	v_addc_co_u32_e32 v65, vcc, 0, v51, vcc
	global_load_dwordx4 v[50:53], v[64:65], off offset:3072
	s_waitcnt vmcnt(15)
	v_bcnt_u32_b32 v23, v22, 0
	v_cmp_lt_u32_e32 vcc, 2, v23
	v_cmp_eq_u32_e64 s[42:43], 0, v22
	v_cmp_lt_u32_e64 s[40:41], 1, v23
	s_waitcnt vmcnt(14)
	v_cndmask_b32_e32 v22, v235, v28, vcc
	v_max_f32_e32 v23, v22, v22
	v_max_f32_e32 v24, v30, v30
	s_waitcnt vmcnt(13)
	v_cndmask_b32_e64 v18, v18, v235, s[42:43]
	v_cndmask_b32_e64 v20, v235, v20, s[40:41]
	v_max_f32_e32 v23, v23, v24
	v_max3_f32 v23, v18, v20, v23
	v_sub_f32_e32 v18, v18, v23
	v_exp_f32_e32 v18, v18
	s_waitcnt vmcnt(11)
	v_cndmask_b32_e64 v28, v34, 0, s[42:43]
	v_cndmask_b32_e64 v44, v33, 0, s[42:43]
	v_mul_f32_e32 v18, v19, v18
	v_cndmask_b32_e64 v24, v18, 0, s[42:43]
	v_sub_f32_e32 v18, v20, v23
	v_exp_f32_e32 v18, v18
	s_waitcnt vmcnt(9)
	v_cndmask_b32_e32 v25, 0, v42, vcc
	v_cndmask_b32_e64 v27, 0, v38, s[40:41]
	v_cndmask_b32_e64 v36, 0, v36, s[40:41]
	v_mul_f32_e32 v18, v21, v18
	v_cndmask_b32_e64 v20, 0, v18, s[40:41]
	v_sub_f32_e32 v18, v22, v23
	v_exp_f32_e32 v18, v18
	v_and_b32_e32 v33, 0xffff0000, v6
	v_cndmask_b32_e64 v21, 0, v39, s[40:41]
	v_cndmask_b32_e32 v19, 0, v43, vcc
	v_mul_f32_e32 v18, v29, v18
	v_cndmask_b32_e32 v22, 0, v18, vcc
	v_sub_f32_e32 v18, v30, v23
	v_exp_f32_e32 v18, v18
	v_cndmask_b32_e64 v23, v35, 0, s[42:43]
	v_cndmask_b32_e64 v35, v32, 0, s[42:43]
	v_add_f32_e32 v32, v24, v20
	v_mul_f32_e32 v26, v31, v18
	v_fma_f32 v18, v31, v18, v22
	v_lshlrev_b32_e32 v34, 16, v35
	v_and_b32_e32 v35, 0xffff0000, v35
	v_add_f32_e32 v18, v32, v18
	v_lshlrev_b32_e32 v32, 16, v6
	v_pk_mul_f32 v[34:35], v[24:25], v[34:35] op_sel_hi:[0,1]
	v_cndmask_b32_e64 v30, 0, v37, s[40:41]
	v_cndmask_b32_e32 v37, 0, v40, vcc
	v_pk_fma_f32 v[32:33], v[26:27], v[32:33], v[34:35] op_sel_hi:[0,1,1]
	v_lshlrev_b32_e32 v34, 16, v36
	v_and_b32_e32 v35, 0xffff0000, v36
	v_pk_fma_f32 v[32:33], v[20:21], v[34:35], v[32:33] op_sel_hi:[0,1,1]
	v_lshlrev_b32_e32 v34, 16, v37
	v_and_b32_e32 v35, 0xffff0000, v37
	v_pk_fma_f32 v[32:33], v[22:23], v[34:35], v[32:33] op_sel_hi:[0,1,1]
	s_waitcnt vmcnt(8)
; DI unsigned cvtpk(float lo, float hi) { typedef float f2 __attribute__((ext_vector_type(2))); typedef __bf16 b2 __attribute__((ext_vector_type(2))); f2 v = {lo, hi}; b2 b = __builtin_convertvector(v, b2); return __builtin_bit_cast(unsigned, b); }
; DI float bflo(unsigned w) { return __uint_as_float(w << 16); }
; DI float bfhi(unsigned w) { return __uint_as_float(w & 0xffff0000u); }
; DI float fast_exp2(float x) { return __builtin_amdgcn_exp2f(x); }
; DI float fast_rcp(float x) { return __builtin_amdgcn_rcpf(x); }
; DI float silu_(float g) { return g * fast_rcp(1.f + fast_exp2(-g * LOG2E)); }
; DI void moba_combine_token(bf16_t* act, const unsigned* sel, const float* ml, int tok, int lane) {
;     ...
;     const float w0 = ns > 0 ? a.y * fast_exp2(m0 - M) : 0.f, w1 = ns > 1 ? a.w * fast_exp2(m1 - M) : 0.f, w2 = ns > 2 ? c.y * fast_exp2(m2 - M) : 0.f, w3 = c.w * fast_exp2(m3 - M);
;     const float inv = fast_rcp((w0 + w1) + (w2 + w3));
;     float acc[8];
;     acc[0] = w3 * bflo(v3.x); acc[1] = w3 * bfhi(v3.x); acc[2] = w3 * bflo(v3.y); acc[3] = w3 * bfhi(v3.y); acc[4] = w3 * bflo(v3.z); acc[5] = w3 * bfhi(v3.z); acc[6] = w3 * bflo(v3.w); acc[7] = w3 * bfhi(v3.w);
; #pragma unroll
;     for (int s = 0; s < 3; ++s) {
;         const float w = s == 0 ? w0 : (s == 1 ? w1 : w2);
;         const bool use = s < ns;
;         u32x4 v = vs[s]; if (!use) v = (u32x4){0u, 0u, 0u, 0u};
;         acc[0] += w * bflo(v.x); acc[1] += w * bfhi(v.x); acc[2] += w * bflo(v.y); acc[3] += w * bfhi(v.y); acc[4] += w * bflo(v.z); acc[5] += w * bfhi(v.z); acc[6] += w * bflo(v.w); acc[7] += w * bfhi(v.w);
;     }
;     u32x4 y;
;     y.x = cvtpk(acc[0] * inv * silu_(bflo(g.x)), acc[1] * inv * silu_(bfhi(g.x))); y.y = cvtpk(acc[2] * inv * silu_(bflo(g.y)), acc[3] * inv * silu_(bfhi(g.y)));
;     y.z = cvtpk(acc[4] * inv * silu_(bflo(g.z)), acc[5] * inv * silu_(bfhi(g.z))); y.w = cvtpk(acc[6] * inv * silu_(bflo(g.w)), acc[7] * inv * silu_(bfhi(g.w)));
;     *(u32x4*)(rowp + C_QB + hh * 64 + ch * 8) = y;
	v_lshlrev_b32_e32 v34, 16, v2
	v_and_b32_e32 v35, 0xffff0000, v2
	v_mul_f32_e32 v2, 0xbfb8aa3b, v34
	v_exp_f32_e32 v2, v2
	v_rcp_f32_e32 v18, v18
	v_lshlrev_b32_e32 v6, 16, v7
	v_and_b32_e32 v7, 0xffff0000, v7
	v_add_f32_e32 v2, 1.0, v2
	v_rcp_f32_e32 v36, v2
	v_mul_f32_e32 v2, 0xbfb8aa3b, v35
	v_exp_f32_e32 v2, v2
	v_pk_mul_f32 v[32:33], v[18:19], v[32:33] op_sel_hi:[0,1]
	v_cndmask_b32_e32 v29, 0, v41, vcc
	v_and_b32_e32 v31, 0xffff0000, v29
	v_add_f32_e32 v2, 1.0, v2
	v_rcp_f32_e32 v37, v2
	s_nop 0
	v_pk_mul_f32 v[34:35], v[36:37], v[34:35]
	s_nop 0
	v_pk_mul_f32 v[32:33], v[34:35], v[32:33]
	s_nop 0
	v_cvt_pk_bf16_f32 v2, v32, v33
	v_lshlrev_b32_e32 v32, 16, v44
	v_and_b32_e32 v33, 0xffff0000, v44
	v_pk_mul_f32 v[32:33], v[24:25], v[32:33] op_sel_hi:[0,1]
	v_pk_fma_f32 v[6:7], v[26:27], v[6:7], v[32:33] op_sel_hi:[0,1,1]
	v_lshlrev_b32_e32 v32, 16, v30
	v_and_b32_e32 v33, 0xffff0000, v30
	v_pk_fma_f32 v[6:7], v[20:21], v[32:33], v[6:7] op_sel_hi:[0,1,1]
	v_lshlrev_b32_e32 v30, 16, v29
	v_pk_fma_f32 v[6:7], v[22:23], v[30:31], v[6:7] op_sel_hi:[0,1,1]
	v_lshlrev_b32_e32 v30, 16, v3
	v_and_b32_e32 v31, 0xffff0000, v3
	v_mul_f32_e32 v3, 0xbfb8aa3b, v30
	v_exp_f32_e32 v3, v3
	v_pk_mul_f32 v[6:7], v[18:19], v[6:7] op_sel_hi:[0,1]
	v_add_f32_e32 v3, 1.0, v3
	v_rcp_f32_e32 v32, v3
	v_mul_f32_e32 v3, 0xbfb8aa3b, v31
	v_exp_f32_e32 v3, v3
	s_nop 0
	v_add_f32_e32 v3, 1.0, v3
	v_rcp_f32_e32 v33, v3
	s_nop 0
	v_pk_mul_f32 v[30:31], v[32:33], v[30:31]
	s_nop 0
	v_pk_mul_f32 v[6:7], v[30:31], v[6:7]
	v_lshlrev_b32_e32 v30, 16, v28
	v_and_b32_e32 v31, 0xffff0000, v28
	v_cvt_pk_bf16_f32 v3, v6, v7
	v_lshlrev_b32_e32 v6, 16, v8
	v_and_b32_e32 v7, 0xffff0000, v8
	v_pk_mul_f32 v[28:29], v[24:25], v[30:31] op_sel_hi:[0,1]
	v_pk_fma_f32 v[6:7], v[26:27], v[6:7], v[28:29] op_sel_hi:[0,1,1]
	v_lshlrev_b32_e32 v28, 16, v27
	v_and_b32_e32 v29, 0xffff0000, v27
	v_pk_fma_f32 v[6:7], v[20:21], v[28:29], v[6:7] op_sel_hi:[0,1,1]
	v_lshlrev_b32_e32 v28, 16, v25
	v_and_b32_e32 v29, 0xffff0000, v25
	v_pk_fma_f32 v[6:7], v[22:23], v[28:29], v[6:7] op_sel_hi:[0,1,1]
	v_lshlrev_b32_e32 v28, 16, v4
	v_and_b32_e32 v29, 0xffff0000, v4
	v_mul_f32_e32 v4, 0xbfb8aa3b, v28
	v_exp_f32_e32 v4, v4
	v_pk_mul_f32 v[6:7], v[18:19], v[6:7] op_sel_hi:[0,1]
	v_lshlrev_b32_e32 v8, 16, v23
	v_add_f32_e32 v4, 1.0, v4
	v_rcp_f32_e32 v30, v4
	v_mul_f32_e32 v4, 0xbfb8aa3b, v29
	v_exp_f32_e32 v4, v4
	s_nop 0
	v_add_f32_e32 v4, 1.0, v4
	v_rcp_f32_e32 v31, v4
	s_nop 0
	v_pk_mul_f32 v[28:29], v[30:31], v[28:29]
	s_nop 0
	v_pk_mul_f32 v[6:7], v[28:29], v[6:7]
	s_nop 0
	v_cvt_pk_bf16_f32 v4, v6, v7
	v_lshlrev_b32_e32 v6, 16, v9
	v_and_b32_e32 v7, 0xffff0000, v9
	v_and_b32_e32 v9, 0xffff0000, v23
	v_pk_mul_f32 v[8:9], v[24:25], v[8:9] op_sel_hi:[0,1]
	v_pk_fma_f32 v[6:7], v[26:27], v[6:7], v[8:9] op_sel_hi:[0,1,1]
	v_lshlrev_b32_e32 v8, 16, v21
	v_and_b32_e32 v9, 0xffff0000, v21
	v_pk_fma_f32 v[6:7], v[20:21], v[8:9], v[6:7] op_sel_hi:[0,1,1]
	v_lshlrev_b32_e32 v8, 16, v19
	v_and_b32_e32 v9, 0xffff0000, v19
	v_pk_fma_f32 v[6:7], v[22:23], v[8:9], v[6:7] op_sel_hi:[0,1,1]
	v_lshlrev_b32_e32 v8, 16, v5
	v_and_b32_e32 v9, 0xffff0000, v5
	v_mul_f32_e32 v5, 0xbfb8aa3b, v8
	v_exp_f32_e32 v5, v5
	v_pk_mul_f32 v[6:7], v[18:19], v[6:7] op_sel_hi:[0,1]
	v_add_f32_e32 v5, 1.0, v5
	v_rcp_f32_e32 v20, v5
	v_mul_f32_e32 v5, 0xbfb8aa3b, v9
	v_exp_f32_e32 v5, v5
	s_nop 0
	v_add_f32_e32 v5, 1.0, v5
	v_rcp_f32_e32 v21, v5
	s_nop 0
	v_pk_mul_f32 v[8:9], v[20:21], v[8:9]
	s_nop 0
	v_pk_mul_f32 v[6:7], v[8:9], v[6:7]
	s_nop 0
	v_cvt_pk_bf16_f32 v5, v6, v7
	global_store_dwordx4 v[16:17], v[2:5], off
	s_cmpk_gt_i32 s8, 0x7fff
	s_cbranch_scc1 .LBB0_582
; DI float bflo(unsigned w) { return __uint_as_float(w << 16); }
; DI float bfhi(unsigned w) { return __uint_as_float(w & 0xffff0000u); }
; DI void moba_combine_token(bf16_t* act, const unsigned* sel, const float* ml, int tok, int lane) {
;     const int hh = lane >> 3, ch = lane & 7;
;     const int b = tok >> 13, qpos = tok & (SEQ - 1);
;     bf16_t* rowp = act + (size_t)tok * PITCH;
;     const unsigned word = sel[(size_t)(b * 8 + hh) * SEQ + qpos];
;     const f32x4* mlp = (const f32x4*)(ml + ((size_t)tok * 8 + hh) * 8);
;     const f32x4 a = mlp[0], c = mlp[1];
;     const u32x4 v3 = *(const u32x4*)(rowp + C_KC + hh * 64 + ch * 8);
;     u32x4 vs[3];
; #pragma unroll
;     for (int s = 0; s < 3; ++s) vs[s] = *(const u32x4*)(rowp + C_KA + (s * 8 + hh) * 64 + ch * 8);
;     const u32x4 g = *(const u32x4*)(rowp + C_GB + hh * 64 + ch * 8);
;     const int ns = __popc(word);
;     const float m0 = ns > 0 ? a.x : NEG_INF, m1 = ns > 1 ? a.z : NEG_INF, m2 = ns > 2 ? c.x : NEG_INF, m3 = c.z;
;     const float M = fmaxf(fmaxf(m0, m1), fmaxf(m2, m3));
;     const float w0 = ns > 0 ? a.y * fast_exp2(m0 - M) : 0.f, w1 = ns > 1 ? a.w * fast_exp2(m1 - M) : 0.f, w2 = ns > 2 ? c.y * fast_exp2(m2 - M) : 0.f, w3 = c.w * fast_exp2(m3 - M);
;     const float inv = fast_rcp((w0 + w1) + (w2 + w3));
;     float acc[8];
;     acc[0] = w3 * bflo(v3.x); acc[1] = w3 * bfhi(v3.x); acc[2] = w3 * bflo(v3.y); acc[3] = w3 * bfhi(v3.y); acc[4] = w3 * bflo(v3.z); acc[5] = w3 * bfhi(v3.z); acc[6] = w3 * bflo(v3.w); acc[7] = w3 * bfhi(v3.w);
; #pragma unroll
;     for (int s = 0; s < 3; ++s) {
;         const float w = s == 0 ? w0 : (s == 1 ? w1 : w2);
;         const bool use = s < ns;
;         u32x4 v = vs[s]; if (!use) v = (u32x4){0u, 0u, 0u, 0u};
;         acc[0] += w * bflo(v.x); acc[1] += w * bfhi(v.x); acc[2] += w * bflo(v.y); acc[3] += w * bfhi(v.y); acc[4] += w * bflo(v.z); acc[5] += w * bfhi(v.z); acc[6] += w * bflo(v.w); acc[7] += w * bfhi(v.w);
;     }
;     u32x4 y;
;     y.x = cvtpk(acc[0] * inv * silu_(bflo(g.x)), acc[1] * inv * silu_(bfhi(g.x))); y.y = cvtpk(acc[2] * inv * silu_(bflo(g.y)), acc[3] * inv * silu_(bfhi(g.y)));
;     y.z = cvtpk(acc[4] * inv * silu_(bflo(g.z)), acc[5] * inv * silu_(bfhi(g.z))); y.w = cvtpk(acc[6] * inv * silu_(bflo(g.w)), acc[7] * inv * silu_(bfhi(g.w)));
;     *(u32x4*)(rowp + C_QB + hh * 64 + ch * 8) = y;
	s_waitcnt vmcnt(6)
	v_cmp_eq_u32_e64 s[42:43], 0, v70
	v_bcnt_u32_b32 v48, v70, 0
	s_nop 0
	v_cmp_lt_u32_e32 vcc, 2, v48
	v_cmp_lt_u32_e64 s[40:41], 1, v48
	s_waitcnt vmcnt(6)
	v_cndmask_b32_e64 v63, v66, v235, s[42:43]
	v_cndmask_b32_e32 v48, v235, v74, vcc
	v_cndmask_b32_e64 v66, v235, v68, s[40:41]
	v_max_f32_e32 v68, v48, v48
	v_max_f32_e32 v70, v76, v76
	v_max_f32_e32 v68, v68, v70
	v_max3_f32 v71, v63, v66, v68
	v_sub_f32_e32 v63, v63, v71
	v_exp_f32_e32 v63, v63
	v_sub_f32_e32 v48, v48, v71
	v_exp_f32_e32 v48, v48
	v_mul_f32_e32 v63, v67, v63
	v_cndmask_b32_e64 v70, v63, 0, s[42:43]
	v_sub_f32_e32 v63, v66, v71
	v_exp_f32_e32 v63, v63
	v_mul_f32_e32 v48, v75, v48
	v_cndmask_b32_e32 v68, 0, v48, vcc
	v_sub_f32_e32 v48, v76, v71
	v_exp_f32_e32 v48, v48
	v_mul_f32_e32 v63, v69, v63
	v_cndmask_b32_e64 v66, 0, v63, s[40:41]
	v_mul_f32_e32 v72, v77, v48
	v_fma_f32 v48, v77, v48, v68
	s_waitcnt vmcnt(4)
	v_cndmask_b32_e64 v69, v81, 0, s[42:43]
	v_cndmask_b32_e64 v81, v78, 0, s[42:43]
	v_cndmask_b32_e64 v74, v80, 0, s[42:43]
	s_waitcnt vmcnt(2)
	v_cndmask_b32_e32 v71, 0, v88, vcc
	v_add_f32_e32 v78, v70, v66
	v_lshlrev_b32_e32 v80, 16, v81
	v_and_b32_e32 v81, 0xffff0000, v81
	v_cndmask_b32_e64 v90, v79, 0, s[42:43]
	v_cndmask_b32_e64 v73, 0, v84, s[40:41]
	v_cndmask_b32_e64 v82, 0, v82, s[40:41]
	v_add_f32_e32 v48, v78, v48
	v_lshlrev_b32_e32 v78, 16, v54
	v_and_b32_e32 v79, 0xffff0000, v54
	v_pk_mul_f32 v[80:81], v[70:71], v[80:81] op_sel_hi:[0,1]
	v_cndmask_b32_e64 v67, 0, v85, s[40:41]
	v_cndmask_b32_e64 v76, 0, v83, s[40:41]
	v_cndmask_b32_e32 v83, 0, v86, vcc
	v_pk_fma_f32 v[78:79], v[72:73], v[78:79], v[80:81] op_sel_hi:[0,1,1]
	v_lshlrev_b32_e32 v80, 16, v82
	v_and_b32_e32 v81, 0xffff0000, v82
	v_pk_fma_f32 v[78:79], v[66:67], v[80:81], v[78:79] op_sel_hi:[0,1,1]
	v_lshlrev_b32_e32 v80, 16, v83
	v_and_b32_e32 v81, 0xffff0000, v83
	v_pk_fma_f32 v[78:79], v[68:69], v[80:81], v[78:79] op_sel_hi:[0,1,1]
	s_waitcnt vmcnt(1)
	v_lshlrev_b32_e32 v80, 16, v50
	v_and_b32_e32 v81, 0xffff0000, v50
	v_mul_f32_e32 v50, 0xbfb8aa3b, v80
	v_exp_f32_e32 v50, v50
	v_rcp_f32_e32 v48, v48
	v_lshlrev_b32_e32 v54, 16, v55
	v_and_b32_e32 v55, 0xffff0000, v55
	v_add_f32_e32 v50, 1.0, v50
	v_rcp_f32_e32 v82, v50
	v_mul_f32_e32 v50, 0xbfb8aa3b, v81
	v_exp_f32_e32 v50, v50
	v_pk_mul_f32 v[78:79], v[48:49], v[78:79] op_sel_hi:[0,1]
	v_cndmask_b32_e32 v75, 0, v87, vcc
	v_and_b32_e32 v77, 0xffff0000, v75
	v_add_f32_e32 v50, 1.0, v50
	v_rcp_f32_e32 v83, v50
	v_cndmask_b32_e32 v63, 0, v89, vcc
	v_pk_mul_f32 v[80:81], v[82:83], v[80:81]
	s_nop 0
	v_pk_mul_f32 v[78:79], v[80:81], v[78:79]
	s_nop 0
	v_cvt_pk_bf16_f32 v50, v78, v79
	v_lshlrev_b32_e32 v78, 16, v90
	v_and_b32_e32 v79, 0xffff0000, v90
	v_pk_mul_f32 v[78:79], v[70:71], v[78:79] op_sel_hi:[0,1]
	v_pk_fma_f32 v[54:55], v[72:73], v[54:55], v[78:79] op_sel_hi:[0,1,1]
	v_lshlrev_b32_e32 v78, 16, v76
	v_and_b32_e32 v79, 0xffff0000, v76
	v_pk_fma_f32 v[54:55], v[66:67], v[78:79], v[54:55] op_sel_hi:[0,1,1]
	v_lshlrev_b32_e32 v76, 16, v75
	v_pk_fma_f32 v[54:55], v[68:69], v[76:77], v[54:55] op_sel_hi:[0,1,1]
	v_lshlrev_b32_e32 v76, 16, v51
	v_and_b32_e32 v77, 0xffff0000, v51
	v_mul_f32_e32 v51, 0xbfb8aa3b, v76
	v_exp_f32_e32 v51, v51
	v_pk_mul_f32 v[54:55], v[48:49], v[54:55] op_sel_hi:[0,1]
	v_add_f32_e32 v51, 1.0, v51
	v_rcp_f32_e32 v78, v51
	v_mul_f32_e32 v51, 0xbfb8aa3b, v77
	v_exp_f32_e32 v51, v51
	s_nop 0
	v_add_f32_e32 v51, 1.0, v51
	v_rcp_f32_e32 v79, v51
	s_nop 0
	v_pk_mul_f32 v[76:77], v[78:79], v[76:77]
	s_nop 0
	v_pk_mul_f32 v[54:55], v[76:77], v[54:55]
	v_lshlrev_b32_e32 v76, 16, v74
	v_and_b32_e32 v77, 0xffff0000, v74
	v_cvt_pk_bf16_f32 v51, v54, v55
	v_lshlrev_b32_e32 v54, 16, v56
	v_and_b32_e32 v55, 0xffff0000, v56
	v_pk_mul_f32 v[74:75], v[70:71], v[76:77] op_sel_hi:[0,1]
	v_pk_fma_f32 v[54:55], v[72:73], v[54:55], v[74:75] op_sel_hi:[0,1,1]
	v_lshlrev_b32_e32 v74, 16, v73
	v_and_b32_e32 v75, 0xffff0000, v73
	v_pk_fma_f32 v[54:55], v[66:67], v[74:75], v[54:55] op_sel_hi:[0,1,1]
	v_lshlrev_b32_e32 v74, 16, v71
	v_and_b32_e32 v75, 0xffff0000, v71
	v_pk_fma_f32 v[54:55], v[68:69], v[74:75], v[54:55] op_sel_hi:[0,1,1]
	v_lshlrev_b32_e32 v74, 16, v52
	v_and_b32_e32 v75, 0xffff0000, v52
	v_mul_f32_e32 v52, 0xbfb8aa3b, v74
	v_exp_f32_e32 v52, v52
	v_pk_mul_f32 v[54:55], v[48:49], v[54:55] op_sel_hi:[0,1]
	v_lshlrev_b32_e32 v56, 16, v69
	v_add_f32_e32 v52, 1.0, v52
	v_rcp_f32_e32 v76, v52
	v_mul_f32_e32 v52, 0xbfb8aa3b, v75
	v_exp_f32_e32 v52, v52
	s_nop 0
	v_add_f32_e32 v52, 1.0, v52
	v_rcp_f32_e32 v77, v52
	s_nop 0
	v_pk_mul_f32 v[74:75], v[76:77], v[74:75]
	s_nop 0
	v_pk_mul_f32 v[54:55], v[74:75], v[54:55]
	s_nop 0
	v_cvt_pk_bf16_f32 v52, v54, v55
	v_lshlrev_b32_e32 v54, 16, v57
	v_and_b32_e32 v55, 0xffff0000, v57
	v_and_b32_e32 v57, 0xffff0000, v69
	v_pk_mul_f32 v[56:57], v[70:71], v[56:57] op_sel_hi:[0,1]
	v_pk_fma_f32 v[54:55], v[72:73], v[54:55], v[56:57] op_sel_hi:[0,1,1]
	v_lshlrev_b32_e32 v56, 16, v67
	v_and_b32_e32 v57, 0xffff0000, v67
	v_pk_fma_f32 v[54:55], v[66:67], v[56:57], v[54:55] op_sel_hi:[0,1,1]
	v_lshlrev_b32_e32 v56, 16, v63
	v_and_b32_e32 v57, 0xffff0000, v63
	v_pk_fma_f32 v[54:55], v[68:69], v[56:57], v[54:55] op_sel_hi:[0,1,1]
	v_lshlrev_b32_e32 v56, 16, v53
	v_and_b32_e32 v57, 0xffff0000, v53
	v_mul_f32_e32 v53, 0xbfb8aa3b, v56
	v_pk_mul_f32 v[54:55], v[48:49], v[54:55] op_sel_hi:[0,1]
	v_mul_f32_e32 v48, 0xbfb8aa3b, v57
	v_exp_f32_e32 v53, v53
	v_exp_f32_e32 v48, v48
	v_add_f32_e32 v53, 1.0, v53
	v_add_f32_e32 v48, 1.0, v48
	v_rcp_f32_e32 v66, v53
	v_rcp_f32_e32 v67, v48
	s_nop 0
	v_pk_mul_f32 v[56:57], v[66:67], v[56:57]
	s_nop 0
	v_pk_mul_f32 v[54:55], v[56:57], v[54:55]
	s_nop 0
	v_cvt_pk_bf16_f32 v53, v54, v55
	global_store_dwordx4 v[64:65], v[50:53], off
	s_branch .LBB0_582
